# in-proj epilogue stores: scalar base + one 32-bit lane offset per tile (per row block 2 v_lshl_add_u64 + 2 v_mad_u64_u32 + 2 v_mov replaced by 3 SALU)
# baseline (speedup 1.0000x reference)
.LBB0_180:
	s_ashr_i32 s29, s28, 31
	s_lshl_b64 s[28:29], s[28:29], 1
	s_add_u32 s96, s30, s28
	s_addc_u32 s97, s31, s29
	v_add_u32_e32 v202, s24, v138
	v_mul_u32_u24_e32 v202, s26, v202
	v_lshl_add_u32 v202, v202, 1, v136
	v_cvt_pk_bf16_f32 v124, v166, v167
	v_cvt_pk_bf16_f32 v125, v168, v169
	v_cvt_pk_bf16_f32 v126, v170, v171
	v_cvt_pk_bf16_f32 v127, v172, v173
	s_cmp_gt_i32 s13, 2
	s_mov_b64 s[28:29], -1
	global_store_dwordx4 v202, v[124:127], s[96:97] nt
	s_cbranch_scc0 .LBB0_182
	s_nop 0
	v_mul_f32_e32 v124, 0xbfb8aa3b, v116
	v_mul_f32_e32 v125, 0xbfb8aa3b, v117
	v_mul_f32_e32 v126, 0xbfb8aa3b, v118
	v_mul_f32_e32 v127, 0xbfb8aa3b, v119
	v_mul_f32_e32 v166, 0xbfb8aa3b, v112
	v_mul_f32_e32 v167, 0xbfb8aa3b, v113
	v_mul_f32_e32 v168, 0xbfb8aa3b, v114
	v_mul_f32_e32 v169, 0xbfb8aa3b, v115
	v_exp_f32_e32 v124, v124
	v_exp_f32_e32 v125, v125
	v_exp_f32_e32 v126, v126
	v_exp_f32_e32 v127, v127
	v_exp_f32_e32 v166, v166
	v_exp_f32_e32 v167, v167
	v_exp_f32_e32 v168, v168
	v_exp_f32_e32 v169, v169
	v_add_f32_e32 v124, 1.0, v124
	v_add_f32_e32 v125, 1.0, v125
	v_add_f32_e32 v126, 1.0, v126
	v_add_f32_e32 v127, 1.0, v127
	v_add_f32_e32 v166, 1.0, v166
	v_add_f32_e32 v167, 1.0, v167
	v_add_f32_e32 v168, 1.0, v168
	v_add_f32_e32 v169, 1.0, v169
	v_rcp_f32_e32 v124, v124
	v_rcp_f32_e32 v125, v125
	v_rcp_f32_e32 v126, v126
	v_rcp_f32_e32 v127, v127
	v_rcp_f32_e32 v166, v166
	v_rcp_f32_e32 v167, v167
	v_rcp_f32_e32 v168, v168
	v_rcp_f32_e32 v169, v169
	s_mov_b64 s[28:29], 0

.LBB0_186:
	v_cvt_pk_bf16_f32 v112, v124, v125
	v_cvt_pk_bf16_f32 v113, v126, v127
	v_cvt_pk_bf16_f32 v114, v166, v167
	v_cvt_pk_bf16_f32 v115, v168, v169
	global_store_dwordx4 v202, v[112:115], s[96:97] offset:256 nt
	s_cmp_gt_i32 s13, 2
	s_mov_b64 s[28:29], -1
	s_cbranch_scc0 .LBB0_188
	v_mul_f32_e32 v112, 0xbfb8aa3b, v108
	v_exp_f32_e32 v112, v112
	v_mul_f32_e32 v113, 0xbfb8aa3b, v109
	v_exp_f32_e32 v113, v113
	v_mul_f32_e32 v115, 0xbfb8aa3b, v111
	v_add_f32_e32 v112, 1.0, v112
	v_rcp_f32_e32 v114, v112
	v_mul_f32_e32 v112, 0xbfb8aa3b, v110
	v_exp_f32_e32 v112, v112
	v_exp_f32_e32 v117, v115
	v_add_f32_e32 v113, 1.0, v113
	v_rcp_f32_e32 v115, v113
	v_add_f32_e32 v112, 1.0, v112
	v_mul_f32_e32 v113, 0xbfb8aa3b, v104
	v_rcp_f32_e32 v116, v112
	v_add_f32_e32 v112, 1.0, v117
	v_exp_f32_e32 v113, v113
	v_mul_f32_e32 v117, 0xbfb8aa3b, v105
	v_exp_f32_e32 v119, v117
	v_rcp_f32_e32 v117, v112
	v_add_f32_e32 v112, 1.0, v113
	v_mul_f32_e32 v113, 0xbfb8aa3b, v106
	v_rcp_f32_e32 v118, v112
	v_add_f32_e32 v112, 1.0, v119
	v_exp_f32_e32 v113, v113
	v_mul_f32_e32 v119, 0xbfb8aa3b, v107
	v_exp_f32_e32 v123, v119
	v_rcp_f32_e32 v119, v112
	v_add_f32_e32 v112, 1.0, v113
	v_rcp_f32_e32 v122, v112
	v_add_f32_e32 v112, 1.0, v123
	v_rcp_f32_e32 v123, v112
	s_mov_b64 s[28:29], 0

.LBB0_192:
	s_mul_i32 s94, s26, 0x20
	s_add_u32 s94, s96, s94
	s_addc_u32 s95, s97, 0
	v_cvt_pk_bf16_f32 v106, v114, v115
	v_cvt_pk_bf16_f32 v107, v116, v117
	v_cvt_pk_bf16_f32 v108, v118, v119
	v_cvt_pk_bf16_f32 v109, v122, v123
	s_cmp_gt_i32 s13, 2
	s_mov_b64 s[28:29], -1
	global_store_dwordx4 v202, v[106:109], s[94:95] nt
	s_cbranch_scc0 .LBB0_194
	s_nop 0
	v_mul_f32_e32 v106, 0xbfb8aa3b, v100
	v_mul_f32_e32 v107, 0xbfb8aa3b, v101
	v_mul_f32_e32 v108, 0xbfb8aa3b, v102
	v_mul_f32_e32 v109, 0xbfb8aa3b, v103
	v_mul_f32_e32 v110, 0xbfb8aa3b, v96
	v_mul_f32_e32 v111, 0xbfb8aa3b, v97
	v_mul_f32_e32 v114, 0xbfb8aa3b, v98
	v_mul_f32_e32 v115, 0xbfb8aa3b, v99
	v_exp_f32_e32 v106, v106
	v_exp_f32_e32 v107, v107
	v_exp_f32_e32 v108, v108
	v_exp_f32_e32 v109, v109
	v_exp_f32_e32 v110, v110
	v_exp_f32_e32 v111, v111
	v_exp_f32_e32 v114, v114
	v_exp_f32_e32 v115, v115
	v_add_f32_e32 v106, 1.0, v106
	v_add_f32_e32 v107, 1.0, v107
	v_add_f32_e32 v108, 1.0, v108
	v_add_f32_e32 v109, 1.0, v109
	v_add_f32_e32 v110, 1.0, v110
	v_add_f32_e32 v111, 1.0, v111
	v_add_f32_e32 v114, 1.0, v114
	v_add_f32_e32 v115, 1.0, v115
	v_rcp_f32_e32 v106, v106
	v_rcp_f32_e32 v107, v107
	v_rcp_f32_e32 v108, v108
	v_rcp_f32_e32 v109, v109
	v_rcp_f32_e32 v110, v110
	v_rcp_f32_e32 v111, v111
	v_rcp_f32_e32 v114, v114
	v_rcp_f32_e32 v115, v115
	s_mov_b64 s[28:29], 0

.LBB0_198:
	v_cvt_pk_bf16_f32 v96, v106, v107
	v_cvt_pk_bf16_f32 v97, v108, v109
	v_cvt_pk_bf16_f32 v98, v110, v111
	v_cvt_pk_bf16_f32 v99, v114, v115
	global_store_dwordx4 v202, v[96:99], s[94:95] offset:256 nt
	s_cmp_gt_i32 s13, 2
	s_mov_b64 s[28:29], -1
	s_cbranch_scc0 .LBB0_200
	v_mul_f32_e32 v96, 0xbfb8aa3b, v92
	v_exp_f32_e32 v96, v96
	v_mul_f32_e32 v97, 0xbfb8aa3b, v93
	v_exp_f32_e32 v97, v97
	v_mul_f32_e32 v99, 0xbfb8aa3b, v95
	v_add_f32_e32 v96, 1.0, v96
	v_rcp_f32_e32 v98, v96
	v_mul_f32_e32 v96, 0xbfb8aa3b, v94
	v_exp_f32_e32 v96, v96
	v_exp_f32_e32 v101, v99
	v_add_f32_e32 v97, 1.0, v97
	v_rcp_f32_e32 v99, v97
	v_add_f32_e32 v96, 1.0, v96
	v_mul_f32_e32 v97, 0xbfb8aa3b, v88
	v_rcp_f32_e32 v100, v96
	v_add_f32_e32 v96, 1.0, v101
	v_exp_f32_e32 v97, v97
	v_mul_f32_e32 v101, 0xbfb8aa3b, v89
	v_exp_f32_e32 v103, v101
	v_rcp_f32_e32 v101, v96
	v_add_f32_e32 v96, 1.0, v97
	v_mul_f32_e32 v97, 0xbfb8aa3b, v90
	v_rcp_f32_e32 v102, v96
	v_add_f32_e32 v96, 1.0, v103
	v_exp_f32_e32 v97, v97
	v_mul_f32_e32 v103, 0xbfb8aa3b, v91
	v_exp_f32_e32 v105, v103
	v_rcp_f32_e32 v103, v96
	v_add_f32_e32 v96, 1.0, v97
	v_rcp_f32_e32 v104, v96
	v_add_f32_e32 v96, 1.0, v105
	v_rcp_f32_e32 v105, v96
	s_mov_b64 s[28:29], 0

.LBB0_204:
	s_mul_i32 s94, s26, 0x40
	s_add_u32 s94, s96, s94
	s_addc_u32 s95, s97, 0
	v_cvt_pk_bf16_f32 v90, v98, v99
	v_cvt_pk_bf16_f32 v91, v100, v101
	v_cvt_pk_bf16_f32 v92, v102, v103
	v_cvt_pk_bf16_f32 v93, v104, v105
	s_cmp_gt_i32 s13, 2
	s_mov_b64 s[28:29], -1
	global_store_dwordx4 v202, v[90:93], s[94:95] nt
	s_cbranch_scc0 .LBB0_206
	s_nop 0
	v_mul_f32_e32 v90, 0xbfb8aa3b, v84
	v_mul_f32_e32 v91, 0xbfb8aa3b, v85
	v_mul_f32_e32 v92, 0xbfb8aa3b, v86
	v_mul_f32_e32 v93, 0xbfb8aa3b, v87
	v_mul_f32_e32 v94, 0xbfb8aa3b, v80
	v_mul_f32_e32 v95, 0xbfb8aa3b, v81
	v_mul_f32_e32 v98, 0xbfb8aa3b, v82
	v_mul_f32_e32 v99, 0xbfb8aa3b, v83
	v_exp_f32_e32 v90, v90
	v_exp_f32_e32 v91, v91
	v_exp_f32_e32 v92, v92
	v_exp_f32_e32 v93, v93
	v_exp_f32_e32 v94, v94
	v_exp_f32_e32 v95, v95
	v_exp_f32_e32 v98, v98
	v_exp_f32_e32 v99, v99
	v_add_f32_e32 v90, 1.0, v90
	v_add_f32_e32 v91, 1.0, v91
	v_add_f32_e32 v92, 1.0, v92
	v_add_f32_e32 v93, 1.0, v93
	v_add_f32_e32 v94, 1.0, v94
	v_add_f32_e32 v95, 1.0, v95
	v_add_f32_e32 v98, 1.0, v98
	v_add_f32_e32 v99, 1.0, v99
	v_rcp_f32_e32 v90, v90
	v_rcp_f32_e32 v91, v91
	v_rcp_f32_e32 v92, v92
	v_rcp_f32_e32 v93, v93
	v_rcp_f32_e32 v94, v94
	v_rcp_f32_e32 v95, v95
	v_rcp_f32_e32 v98, v98
	v_rcp_f32_e32 v99, v99
	s_mov_b64 s[28:29], 0

.LBB0_210:
	v_cvt_pk_bf16_f32 v80, v90, v91
	v_cvt_pk_bf16_f32 v81, v92, v93
	v_cvt_pk_bf16_f32 v82, v94, v95
	v_cvt_pk_bf16_f32 v83, v98, v99
	global_store_dwordx4 v202, v[80:83], s[94:95] offset:256 nt
	s_cmp_gt_i32 s13, 2
	s_mov_b64 s[28:29], -1
	s_cbranch_scc0 .LBB0_212
	v_mul_f32_e32 v80, 0xbfb8aa3b, v76
	v_exp_f32_e32 v80, v80
	v_mul_f32_e32 v81, 0xbfb8aa3b, v77
	v_exp_f32_e32 v81, v81
	v_mul_f32_e32 v83, 0xbfb8aa3b, v79
	v_add_f32_e32 v80, 1.0, v80
	v_rcp_f32_e32 v82, v80
	v_mul_f32_e32 v80, 0xbfb8aa3b, v78
	v_exp_f32_e32 v80, v80
	v_exp_f32_e32 v85, v83
	v_add_f32_e32 v81, 1.0, v81
	v_rcp_f32_e32 v83, v81
	v_add_f32_e32 v80, 1.0, v80
	v_mul_f32_e32 v81, 0xbfb8aa3b, v72
	v_rcp_f32_e32 v84, v80
	v_add_f32_e32 v80, 1.0, v85
	v_exp_f32_e32 v81, v81
	v_mul_f32_e32 v85, 0xbfb8aa3b, v73
	v_exp_f32_e32 v87, v85
	v_rcp_f32_e32 v85, v80
	v_add_f32_e32 v80, 1.0, v81
	v_mul_f32_e32 v81, 0xbfb8aa3b, v74
	v_rcp_f32_e32 v86, v80
	v_add_f32_e32 v80, 1.0, v87
	v_exp_f32_e32 v81, v81
	v_mul_f32_e32 v87, 0xbfb8aa3b, v75
	v_exp_f32_e32 v89, v87
	v_rcp_f32_e32 v87, v80
	v_add_f32_e32 v80, 1.0, v81
	v_rcp_f32_e32 v88, v80
	v_add_f32_e32 v80, 1.0, v89
	v_rcp_f32_e32 v89, v80
	s_mov_b64 s[28:29], 0

.LBB0_216:
	s_mul_i32 s94, s26, 0x60
	s_add_u32 s94, s96, s94
	s_addc_u32 s95, s97, 0
	v_cvt_pk_bf16_f32 v74, v82, v83
	v_cvt_pk_bf16_f32 v75, v84, v85
	v_cvt_pk_bf16_f32 v76, v86, v87
	v_cvt_pk_bf16_f32 v77, v88, v89
	s_cmp_gt_i32 s13, 2
	s_mov_b64 s[28:29], -1
	global_store_dwordx4 v202, v[74:77], s[94:95] nt
	s_cbranch_scc0 .LBB0_218
	s_nop 0
	v_mul_f32_e32 v74, 0xbfb8aa3b, v68
	v_mul_f32_e32 v75, 0xbfb8aa3b, v69
	v_mul_f32_e32 v76, 0xbfb8aa3b, v70
	v_mul_f32_e32 v77, 0xbfb8aa3b, v71
	v_mul_f32_e32 v78, 0xbfb8aa3b, v64
	v_mul_f32_e32 v79, 0xbfb8aa3b, v65
	v_mul_f32_e32 v82, 0xbfb8aa3b, v66
	v_mul_f32_e32 v83, 0xbfb8aa3b, v67
	v_exp_f32_e32 v74, v74
	v_exp_f32_e32 v75, v75
	v_exp_f32_e32 v76, v76
	v_exp_f32_e32 v77, v77
	v_exp_f32_e32 v78, v78
	v_exp_f32_e32 v79, v79
	v_exp_f32_e32 v82, v82
	v_exp_f32_e32 v83, v83
	v_add_f32_e32 v74, 1.0, v74
	v_add_f32_e32 v75, 1.0, v75
	v_add_f32_e32 v76, 1.0, v76
	v_add_f32_e32 v77, 1.0, v77
	v_add_f32_e32 v78, 1.0, v78
	v_add_f32_e32 v79, 1.0, v79
	v_add_f32_e32 v82, 1.0, v82
	v_add_f32_e32 v83, 1.0, v83
	v_rcp_f32_e32 v74, v74
	v_rcp_f32_e32 v75, v75
	v_rcp_f32_e32 v76, v76
	v_rcp_f32_e32 v77, v77
	v_rcp_f32_e32 v78, v78
	v_rcp_f32_e32 v79, v79
	v_rcp_f32_e32 v82, v82
	v_rcp_f32_e32 v83, v83
	s_mov_b64 s[28:29], 0

.LBB0_222:
	v_cvt_pk_bf16_f32 v64, v74, v75
	v_cvt_pk_bf16_f32 v65, v76, v77
	v_cvt_pk_bf16_f32 v66, v78, v79
	v_cvt_pk_bf16_f32 v67, v82, v83
	global_store_dwordx4 v202, v[64:67], s[94:95] offset:256 nt
	s_cmp_gt_i32 s13, 2
	s_mov_b64 s[28:29], -1
	s_cbranch_scc0 .LBB0_224
	v_mul_f32_e32 v64, 0xbfb8aa3b, v60
	v_exp_f32_e32 v64, v64
	v_mul_f32_e32 v65, 0xbfb8aa3b, v61
	v_exp_f32_e32 v65, v65
	v_mul_f32_e32 v67, 0xbfb8aa3b, v63
	v_add_f32_e32 v64, 1.0, v64
	v_rcp_f32_e32 v66, v64
	v_mul_f32_e32 v64, 0xbfb8aa3b, v62
	v_exp_f32_e32 v64, v64
	v_exp_f32_e32 v69, v67
	v_add_f32_e32 v65, 1.0, v65
	v_rcp_f32_e32 v67, v65
	v_add_f32_e32 v64, 1.0, v64
	v_mul_f32_e32 v65, 0xbfb8aa3b, v56
	v_rcp_f32_e32 v68, v64
	v_add_f32_e32 v64, 1.0, v69
	v_exp_f32_e32 v65, v65
	v_mul_f32_e32 v69, 0xbfb8aa3b, v57
	v_exp_f32_e32 v71, v69
	v_rcp_f32_e32 v69, v64
	v_add_f32_e32 v64, 1.0, v65
	v_mul_f32_e32 v65, 0xbfb8aa3b, v58
	v_rcp_f32_e32 v70, v64
	v_add_f32_e32 v64, 1.0, v71
	v_exp_f32_e32 v65, v65
	v_mul_f32_e32 v71, 0xbfb8aa3b, v59
	v_exp_f32_e32 v73, v71
	v_rcp_f32_e32 v71, v64
	v_add_f32_e32 v64, 1.0, v65
	v_rcp_f32_e32 v72, v64
	v_add_f32_e32 v64, 1.0, v73
	v_rcp_f32_e32 v73, v64
	s_mov_b64 s[28:29], 0

.LBB0_228:
	s_mul_i32 s94, s26, 0x100
	s_add_u32 s94, s96, s94
	s_addc_u32 s95, s97, 0
	v_cvt_pk_bf16_f32 v58, v66, v67
	v_cvt_pk_bf16_f32 v59, v68, v69
	v_cvt_pk_bf16_f32 v60, v70, v71
	v_cvt_pk_bf16_f32 v61, v72, v73
	s_cmp_gt_i32 s13, 2
	s_mov_b64 s[28:29], -1
	global_store_dwordx4 v202, v[58:61], s[94:95] nt
	s_cbranch_scc0 .LBB0_230
	s_nop 0
	v_mul_f32_e32 v58, 0xbfb8aa3b, v52
	v_mul_f32_e32 v59, 0xbfb8aa3b, v53
	v_mul_f32_e32 v60, 0xbfb8aa3b, v54
	v_mul_f32_e32 v61, 0xbfb8aa3b, v55
	v_mul_f32_e32 v62, 0xbfb8aa3b, v48
	v_mul_f32_e32 v63, 0xbfb8aa3b, v49
	v_mul_f32_e32 v66, 0xbfb8aa3b, v50
	v_mul_f32_e32 v67, 0xbfb8aa3b, v51
	v_exp_f32_e32 v58, v58
	v_exp_f32_e32 v59, v59
	v_exp_f32_e32 v60, v60
	v_exp_f32_e32 v61, v61
	v_exp_f32_e32 v62, v62
	v_exp_f32_e32 v63, v63
	v_exp_f32_e32 v66, v66
	v_exp_f32_e32 v67, v67
	v_add_f32_e32 v58, 1.0, v58
	v_add_f32_e32 v59, 1.0, v59
	v_add_f32_e32 v60, 1.0, v60
	v_add_f32_e32 v61, 1.0, v61
	v_add_f32_e32 v62, 1.0, v62
	v_add_f32_e32 v63, 1.0, v63
	v_add_f32_e32 v66, 1.0, v66
	v_add_f32_e32 v67, 1.0, v67
	v_rcp_f32_e32 v58, v58
	v_rcp_f32_e32 v59, v59
	v_rcp_f32_e32 v60, v60
	v_rcp_f32_e32 v61, v61
	v_rcp_f32_e32 v62, v62
	v_rcp_f32_e32 v63, v63
	v_rcp_f32_e32 v66, v66
	v_rcp_f32_e32 v67, v67
	s_mov_b64 s[28:29], 0

.LBB0_234:
	v_cvt_pk_bf16_f32 v48, v58, v59
	v_cvt_pk_bf16_f32 v49, v60, v61
	v_cvt_pk_bf16_f32 v50, v62, v63
	v_cvt_pk_bf16_f32 v51, v66, v67
	global_store_dwordx4 v202, v[48:51], s[94:95] offset:256 nt
	s_cmp_gt_i32 s13, 2
	s_mov_b64 s[28:29], -1
	s_cbranch_scc0 .LBB0_236
	v_mul_f32_e32 v48, 0xbfb8aa3b, v44
	v_exp_f32_e32 v48, v48
	v_mul_f32_e32 v49, 0xbfb8aa3b, v45
	v_exp_f32_e32 v49, v49
	v_mul_f32_e32 v51, 0xbfb8aa3b, v47
	v_add_f32_e32 v48, 1.0, v48
	v_rcp_f32_e32 v50, v48
	v_mul_f32_e32 v48, 0xbfb8aa3b, v46
	v_exp_f32_e32 v48, v48
	v_exp_f32_e32 v53, v51
	v_add_f32_e32 v49, 1.0, v49
	v_rcp_f32_e32 v51, v49
	v_add_f32_e32 v48, 1.0, v48
	v_mul_f32_e32 v49, 0xbfb8aa3b, v40
	v_rcp_f32_e32 v52, v48
	v_add_f32_e32 v48, 1.0, v53
	v_exp_f32_e32 v49, v49
	v_mul_f32_e32 v53, 0xbfb8aa3b, v41
	v_exp_f32_e32 v55, v53
	v_rcp_f32_e32 v53, v48
	v_add_f32_e32 v48, 1.0, v49
	v_mul_f32_e32 v49, 0xbfb8aa3b, v42
	v_rcp_f32_e32 v54, v48
	v_add_f32_e32 v48, 1.0, v55
	v_exp_f32_e32 v49, v49
	v_mul_f32_e32 v55, 0xbfb8aa3b, v43
	v_exp_f32_e32 v57, v55
	v_rcp_f32_e32 v55, v48
	v_add_f32_e32 v48, 1.0, v49
	v_rcp_f32_e32 v56, v48
	v_add_f32_e32 v48, 1.0, v57
	v_rcp_f32_e32 v57, v48
	s_mov_b64 s[28:29], 0

.LBB0_240:
	s_mul_i32 s94, s26, 0x120
	s_add_u32 s94, s96, s94
	s_addc_u32 s95, s97, 0
	v_cvt_pk_bf16_f32 v42, v50, v51
	v_cvt_pk_bf16_f32 v43, v52, v53
	v_cvt_pk_bf16_f32 v44, v54, v55
	v_cvt_pk_bf16_f32 v45, v56, v57
	s_cmp_gt_i32 s13, 2
	s_mov_b64 s[28:29], -1
	global_store_dwordx4 v202, v[42:45], s[94:95] nt
	s_cbranch_scc0 .LBB0_242
	s_nop 0
	v_mul_f32_e32 v42, 0xbfb8aa3b, v36
	v_mul_f32_e32 v43, 0xbfb8aa3b, v37
	v_mul_f32_e32 v44, 0xbfb8aa3b, v38
	v_mul_f32_e32 v45, 0xbfb8aa3b, v39
	v_mul_f32_e32 v46, 0xbfb8aa3b, v32
	v_mul_f32_e32 v47, 0xbfb8aa3b, v33
	v_mul_f32_e32 v50, 0xbfb8aa3b, v34
	v_mul_f32_e32 v51, 0xbfb8aa3b, v35
	v_exp_f32_e32 v42, v42
	v_exp_f32_e32 v43, v43
	v_exp_f32_e32 v44, v44
	v_exp_f32_e32 v45, v45
	v_exp_f32_e32 v46, v46
	v_exp_f32_e32 v47, v47
	v_exp_f32_e32 v50, v50
	v_exp_f32_e32 v51, v51
	v_add_f32_e32 v42, 1.0, v42
	v_add_f32_e32 v43, 1.0, v43
	v_add_f32_e32 v44, 1.0, v44
	v_add_f32_e32 v45, 1.0, v45
	v_add_f32_e32 v46, 1.0, v46
	v_add_f32_e32 v47, 1.0, v47
	v_add_f32_e32 v50, 1.0, v50
	v_add_f32_e32 v51, 1.0, v51
	v_rcp_f32_e32 v42, v42
	v_rcp_f32_e32 v43, v43
	v_rcp_f32_e32 v44, v44
	v_rcp_f32_e32 v45, v45
	v_rcp_f32_e32 v46, v46
	v_rcp_f32_e32 v47, v47
	v_rcp_f32_e32 v50, v50
	v_rcp_f32_e32 v51, v51
	s_mov_b64 s[28:29], 0

.LBB0_246:
	v_cvt_pk_bf16_f32 v32, v42, v43
	v_cvt_pk_bf16_f32 v33, v44, v45
	v_cvt_pk_bf16_f32 v34, v46, v47
	v_cvt_pk_bf16_f32 v35, v50, v51
	global_store_dwordx4 v202, v[32:35], s[94:95] offset:256 nt
	s_cmp_gt_i32 s13, 2
	s_mov_b64 s[28:29], -1
	s_cbranch_scc0 .LBB0_248
	v_mul_f32_e32 v32, 0xbfb8aa3b, v28
	v_exp_f32_e32 v32, v32
	v_mul_f32_e32 v33, 0xbfb8aa3b, v29
	v_exp_f32_e32 v33, v33
	v_mul_f32_e32 v35, 0xbfb8aa3b, v31
	v_add_f32_e32 v32, 1.0, v32
	v_rcp_f32_e32 v34, v32
	v_mul_f32_e32 v32, 0xbfb8aa3b, v30
	v_exp_f32_e32 v32, v32
	v_exp_f32_e32 v37, v35
	v_add_f32_e32 v33, 1.0, v33
	v_rcp_f32_e32 v35, v33
	v_add_f32_e32 v32, 1.0, v32
	v_mul_f32_e32 v33, 0xbfb8aa3b, v24
	v_rcp_f32_e32 v36, v32
	v_add_f32_e32 v32, 1.0, v37
	v_exp_f32_e32 v33, v33
	v_mul_f32_e32 v37, 0xbfb8aa3b, v25
	v_exp_f32_e32 v39, v37
	v_rcp_f32_e32 v37, v32
	v_add_f32_e32 v32, 1.0, v33
	v_mul_f32_e32 v33, 0xbfb8aa3b, v26
	v_rcp_f32_e32 v38, v32
	v_add_f32_e32 v32, 1.0, v39
	v_exp_f32_e32 v33, v33
	v_mul_f32_e32 v39, 0xbfb8aa3b, v27
	v_exp_f32_e32 v41, v39
	v_rcp_f32_e32 v39, v32
	v_add_f32_e32 v32, 1.0, v33
	v_rcp_f32_e32 v40, v32
	v_add_f32_e32 v32, 1.0, v41
	v_rcp_f32_e32 v41, v32
	s_mov_b64 s[28:29], 0

.LBB0_252:
	s_mul_i32 s94, s26, 0x140
	s_add_u32 s94, s96, s94
	s_addc_u32 s95, s97, 0
	v_cvt_pk_bf16_f32 v26, v34, v35
	v_cvt_pk_bf16_f32 v27, v36, v37
	v_cvt_pk_bf16_f32 v28, v38, v39
	v_cvt_pk_bf16_f32 v29, v40, v41
	s_cmp_gt_i32 s13, 2
	s_mov_b64 s[28:29], -1
	global_store_dwordx4 v202, v[26:29], s[94:95] nt
	s_cbranch_scc0 .LBB0_254
	s_nop 0
	v_mul_f32_e32 v26, 0xbfb8aa3b, v20
	v_mul_f32_e32 v27, 0xbfb8aa3b, v21
	v_mul_f32_e32 v28, 0xbfb8aa3b, v22
	v_mul_f32_e32 v29, 0xbfb8aa3b, v23
	v_mul_f32_e32 v30, 0xbfb8aa3b, v16
	v_mul_f32_e32 v31, 0xbfb8aa3b, v17
	v_mul_f32_e32 v34, 0xbfb8aa3b, v18
	v_mul_f32_e32 v35, 0xbfb8aa3b, v19
	v_exp_f32_e32 v26, v26
	v_exp_f32_e32 v27, v27
	v_exp_f32_e32 v28, v28
	v_exp_f32_e32 v29, v29
	v_exp_f32_e32 v30, v30
	v_exp_f32_e32 v31, v31
	v_exp_f32_e32 v34, v34
	v_exp_f32_e32 v35, v35
	v_add_f32_e32 v26, 1.0, v26
	v_add_f32_e32 v27, 1.0, v27
	v_add_f32_e32 v28, 1.0, v28
	v_add_f32_e32 v29, 1.0, v29
	v_add_f32_e32 v30, 1.0, v30
	v_add_f32_e32 v31, 1.0, v31
	v_add_f32_e32 v34, 1.0, v34
	v_add_f32_e32 v35, 1.0, v35
	v_rcp_f32_e32 v26, v26
	v_rcp_f32_e32 v27, v27
	v_rcp_f32_e32 v28, v28
	v_rcp_f32_e32 v29, v29
	v_rcp_f32_e32 v30, v30
	v_rcp_f32_e32 v31, v31
	v_rcp_f32_e32 v34, v34
	v_rcp_f32_e32 v35, v35
	s_mov_b64 s[28:29], 0

.LBB0_258:
	v_cvt_pk_bf16_f32 v16, v26, v27
	v_cvt_pk_bf16_f32 v17, v28, v29
	v_cvt_pk_bf16_f32 v18, v30, v31
	v_cvt_pk_bf16_f32 v19, v34, v35
	global_store_dwordx4 v202, v[16:19], s[94:95] offset:256 nt
	s_cmp_gt_i32 s13, 2
	s_mov_b64 s[28:29], -1
	s_cbranch_scc0 .LBB0_260
	v_mul_f32_e32 v16, 0xbfb8aa3b, v12
	v_exp_f32_e32 v16, v16
	v_mul_f32_e32 v17, 0xbfb8aa3b, v13
	v_exp_f32_e32 v17, v17
	v_mul_f32_e32 v19, 0xbfb8aa3b, v15
	v_add_f32_e32 v16, 1.0, v16
	v_rcp_f32_e32 v18, v16
	v_mul_f32_e32 v16, 0xbfb8aa3b, v14
	v_exp_f32_e32 v16, v16
	v_exp_f32_e32 v21, v19
	v_add_f32_e32 v17, 1.0, v17
	v_rcp_f32_e32 v19, v17
	v_add_f32_e32 v16, 1.0, v16
	v_mul_f32_e32 v17, 0xbfb8aa3b, v8
	v_rcp_f32_e32 v20, v16
	v_add_f32_e32 v16, 1.0, v21
	v_exp_f32_e32 v17, v17
	v_mul_f32_e32 v21, 0xbfb8aa3b, v9
	v_exp_f32_e32 v23, v21
	v_rcp_f32_e32 v21, v16
	v_add_f32_e32 v16, 1.0, v17
	v_mul_f32_e32 v17, 0xbfb8aa3b, v10
	v_rcp_f32_e32 v22, v16
	v_add_f32_e32 v16, 1.0, v23
	v_exp_f32_e32 v17, v17
	v_mul_f32_e32 v23, 0xbfb8aa3b, v11
	v_exp_f32_e32 v25, v23
	v_rcp_f32_e32 v23, v16
	v_add_f32_e32 v16, 1.0, v17
	v_rcp_f32_e32 v24, v16
	v_add_f32_e32 v16, 1.0, v25
	v_rcp_f32_e32 v25, v16
	s_mov_b64 s[28:29], 0

.LBB0_264:
	s_mul_i32 s94, s26, 0x160
	s_add_u32 s94, s96, s94
	s_addc_u32 s95, s97, 0
	v_cvt_pk_bf16_f32 v10, v18, v19
	v_cvt_pk_bf16_f32 v11, v20, v21
	v_cvt_pk_bf16_f32 v12, v22, v23
	v_cvt_pk_bf16_f32 v13, v24, v25
	s_cmp_gt_i32 s13, 2
	s_mov_b64 s[24:25], -1
	global_store_dwordx4 v202, v[10:13], s[94:95] nt
	s_cbranch_scc0 .LBB0_266
	s_nop 0
	v_mul_f32_e32 v10, 0xbfb8aa3b, v4
	v_mul_f32_e32 v11, 0xbfb8aa3b, v5
	v_mul_f32_e32 v12, 0xbfb8aa3b, v6
	v_mul_f32_e32 v13, 0xbfb8aa3b, v7
	v_mul_f32_e32 v14, 0xbfb8aa3b, v0
	v_mul_f32_e32 v15, 0xbfb8aa3b, v1
	v_mul_f32_e32 v18, 0xbfb8aa3b, v2
	v_mul_f32_e32 v19, 0xbfb8aa3b, v3
	v_exp_f32_e32 v10, v10
	v_exp_f32_e32 v11, v11
	v_exp_f32_e32 v12, v12
	v_exp_f32_e32 v13, v13
	v_exp_f32_e32 v14, v14
	v_exp_f32_e32 v15, v15
	v_exp_f32_e32 v18, v18
	v_exp_f32_e32 v19, v19
	v_add_f32_e32 v10, 1.0, v10
	v_add_f32_e32 v11, 1.0, v11
	v_add_f32_e32 v12, 1.0, v12
	v_add_f32_e32 v13, 1.0, v13
	v_add_f32_e32 v14, 1.0, v14
	v_add_f32_e32 v15, 1.0, v15
	v_add_f32_e32 v18, 1.0, v18
	v_add_f32_e32 v19, 1.0, v19
	v_rcp_f32_e32 v10, v10
	v_rcp_f32_e32 v11, v11
	v_rcp_f32_e32 v12, v12
	v_rcp_f32_e32 v13, v13
	v_rcp_f32_e32 v14, v14
	v_rcp_f32_e32 v15, v15
	v_rcp_f32_e32 v18, v18
	v_rcp_f32_e32 v19, v19
	s_mov_b64 s[24:25], 0

.LBB0_270:
	v_cvt_pk_bf16_f32 v0, v10, v11
	v_cvt_pk_bf16_f32 v1, v12, v13
	v_cvt_pk_bf16_f32 v2, v14, v15
	v_cvt_pk_bf16_f32 v3, v18, v19
	global_store_dwordx4 v202, v[0:3], s[94:95] offset:256 nt
	s_andn2_b64 vcc, exec, s[16:17]
	s_mov_b64 s[16:17], -1
	s_cbranch_vccnz .LBB0_146
	s_andn2_b64 vcc, exec, s[6:7]
	s_cbranch_vccnz .LBB0_145
	s_barrier
	s_branch .LBB0_145
